# hyconv: shifted filter copies built from wide LDS reads + v_alignbit (no guarded ds_read_u16 chains)
# speedup vs baseline: 1.0043x; 1.0043x over previous
; __device__ __forceinline__ unsigned pack2(float a, float b) { unsigned r; asm("v_cvt_pk_bf16_f32 %0, %1, %2" : "=v"(r) : "v"(a), "v"(b)); return r; }
; __device__ __forceinline__ float bf2f(bf16_t h) { return __uint_as_float(((unsigned)h) << 16); }
; __device__ __forceinline__ void phase_hyconv(CP& p, char* smem) {
;     ...
;       for (int i = 0; i < 8; ++i) {
;         const int q = tid + 256 * i; const int b = q >> 8, l8 = q & 255; const int m1 = l8 >> 3, m2 = (l8 & 7) * 8;
;         const int l0 = l8 * 8;
;         const bf16_t* z2 = p.vvT + (size_t)c * 16384 + b * 2048;
;         const bf16_t* zv = p.vvT + (size_t)(1024 + c) * 16384 + b * 2048;
;         const uint4 u2 = *(const uint4*)(z2 + l0), uv = *(const uint4*)(zv + l0);
;         float e2[10], ev[10];
;         const int lp = l0 > 0 ? l0 - 1 : 0, ln = l0 + 8 < 2048 ? l0 + 8 : 2047;
;         const float pm = l0 > 0 ? 1.f : 0.f, nm = l0 + 8 < 2048 ? 1.f : 0.f;
;         const bf16_t q2p = z2[lp], qvp = zv[lp], q2n = z2[ln], qvn = zv[ln];
;         e2[0] = bf2f(q2p) * pm; ev[0] = bf2f(qvp) * pm;
;         e2[9] = bf2f(q2n) * nm; ev[9] = bf2f(qvn) * nm;
;         const unsigned w2[4] = {u2.x, u2.y, u2.z, u2.w}, wv[4] = {uv.x, uv.y, uv.z, uv.w};
; #pragma unroll
;         for (int j = 0; j < 4; ++j) {
;           e2[1 + 2 * j] = __uint_as_float(w2[j] << 16); e2[2 + 2 * j] = __uint_as_float(w2[j] & 0xffff0000u);
;           ev[1 + 2 * j] = __uint_as_float(wv[j] << 16); ev[2 + 2 * j] = __uint_as_float(wv[j] & 0xffff0000u);
;         }
;         unsigned o[4];
; #pragma unroll
;         for (int j = 0; j < 4; ++j) {
;           const float xa = a0 * e2[2 * j] + a1 * e2[2 * j + 1] + a2 * e2[2 * j + 2] + ab;
;           const float xb = a0 * e2[2 * j + 1] + a1 * e2[2 * j + 2] + a2 * e2[2 * j + 3] + ab;
;           const float ya = v0 * ev[2 * j] + v1 * ev[2 * j + 1] + v2 * ev[2 * j + 2] + vb;
;           const float yb = v0 * ev[2 * j + 1] + v1 * ev[2 * j + 2] + v2 * ev[2 * j + 3] + vb;
;           o[j] = pack2(xa * ya, xb * yb);
;         }
;         uint4 ou; ou.x = o[0]; ou.y = o[1]; ou.z = o[2]; ou.w = o[3];
;         *(uint4*)(Vl + (8 + m1 * 8 + b) * 80 + m2) = ou;
.LBB0_2852:
	v_add_u32_e32 v15, s51, v101
	v_ashrrev_i32_e32 v17, 8, v15
	v_add_u32_e32 v15, 0x100, v15
	v_lshlrev_b32_e32 v16, 11, v17
	v_add_u32_e32 v18, v127, v17
	v_ashrrev_i32_e32 v15, 8, v15
	v_ashrrev_i32_e32 v17, 31, v16
	v_mad_u64_u32 v[32:33], s[74:75], v18, s3, v[100:101]
	v_lshlrev_b32_e32 v18, 11, v15
	v_lshlrev_b64 v[16:17], 1, v[16:17]
	v_ashrrev_i32_e32 v19, 31, v18
	v_add_u32_e32 v15, v127, v15
	v_lshl_add_u64 v[20:21], s[46:47], 0, v[16:17]
	v_lshl_add_u64 v[16:17], s[48:49], 0, v[16:17]
	v_lshlrev_b64 v[18:19], 1, v[18:19]
	v_mad_u64_u32 v[34:35], s[74:75], v15, s3, v[100:101]
	v_lshl_add_u64 v[22:23], v[20:21], 0, v[118:119]
	v_lshl_add_u64 v[24:25], v[16:17], 0, v[118:119]
	v_lshl_add_u64 v[26:27], v[20:21], 0, v[120:121]
	v_lshl_add_u64 v[28:29], v[16:17], 0, v[120:121]
	v_lshl_add_u64 v[20:21], v[20:21], 0, v[122:123]
	v_lshl_add_u64 v[16:17], v[16:17], 0, v[122:123]
	v_lshl_add_u64 v[30:31], s[46:47], 0, v[18:19]
	v_lshl_add_u64 v[36:37], s[48:49], 0, v[18:19]
	global_load_ushort v15, v[26:27], off
	global_load_ushort v33, v[28:29], off
	global_load_ushort v35, v[20:21], off
	global_load_ushort v40, v[16:17], off
	s_nop 0
	global_load_dwordx4 v[16:19], v[22:23], off
	s_nop 0
	global_load_dwordx4 v[20:23], v[24:25], off
	v_lshl_add_u64 v[24:25], v[30:31], 0, v[118:119]
	v_lshl_add_u64 v[28:29], v[36:37], 0, v[118:119]
	v_lshl_add_u64 v[26:27], v[30:31], 0, v[120:121]
	v_lshl_add_u64 v[38:39], v[36:37], 0, v[120:121]
	v_lshl_add_u64 v[30:31], v[30:31], 0, v[122:123]
	v_lshl_add_u64 v[36:37], v[36:37], 0, v[122:123]
	global_load_ushort v41, v[26:27], off
	s_nop 0
	global_load_ushort v38, v[38:39], off
	s_nop 0
	global_load_ushort v39, v[30:31], off
	s_nop 0
	global_load_ushort v36, v[36:37], off
	s_nop 0
	global_load_dwordx4 v[24:27], v[24:25], off
	s_nop 0
	global_load_dwordx4 v[28:31], v[28:29], off
	s_addk_i32 s51, 0x200
	s_cmpk_eq_i32 s51, 0x800
	s_waitcnt vmcnt(11)
	v_lshlrev_b32_e32 v15, 16, v15
	s_waitcnt vmcnt(10)
	v_lshlrev_b32_e32 v33, 16, v33
	v_mul_f32_e32 v15, v125, v15
	s_waitcnt vmcnt(8)
	v_lshlrev_b32_e32 v37, 16, v40
	s_waitcnt vmcnt(7)
	v_lshlrev_b32_e32 v40, 16, v16
	v_and_b32_e32 v16, 0xffff0000, v16
	s_waitcnt vmcnt(6)
	v_lshlrev_b32_e32 v42, 16, v20
	v_and_b32_e32 v20, 0xffff0000, v20
	v_lshlrev_b32_e32 v43, 16, v17
	v_and_b32_e32 v17, 0xffff0000, v17
	v_lshlrev_b32_e32 v44, 16, v21
	v_and_b32_e32 v21, 0xffff0000, v21
	v_lshlrev_b32_e32 v45, 16, v18
	v_and_b32_e32 v18, 0xffff0000, v18
	v_lshlrev_b32_e32 v46, 16, v22
	v_and_b32_e32 v22, 0xffff0000, v22
	v_lshlrev_b32_e32 v47, 16, v19
	v_lshlrev_b32_e32 v48, 16, v23
	v_and_b32_e32 v19, 0xffff0000, v19
	v_and_b32_e32 v23, 0xffff0000, v23
	v_mul_f32_e32 v33, v125, v33
	v_mul_f32_e32 v49, v11, v16
	v_mul_f32_e32 v50, v5, v20
	v_mul_f32_e32 v51, v11, v43
	v_mul_f32_e32 v52, v11, v17
	v_mul_f32_e32 v53, v5, v44
	v_mul_f32_e32 v54, v5, v21
	v_mul_f32_e32 v55, v11, v45
	v_mul_f32_e32 v56, v11, v18
	v_mul_f32_e32 v57, v5, v46
	v_mul_f32_e32 v58, v5, v22
	v_mul_f32_e32 v59, v11, v47
	v_mul_f32_e32 v61, v5, v48
	s_waitcnt vmcnt(5)
	v_lshlrev_b32_e32 v41, 16, v41
	s_waitcnt vmcnt(4)
	v_lshlrev_b32_e32 v38, 16, v38
	s_waitcnt vmcnt(1)
	v_lshlrev_b32_e32 v65, 16, v25
	v_and_b32_e32 v25, 0xffff0000, v25
	s_waitcnt vmcnt(0)
	v_lshlrev_b32_e32 v66, 16, v29
	v_and_b32_e32 v29, 0xffff0000, v29
	v_lshlrev_b32_e32 v35, 16, v35
	v_mul_f32_e32 v60, v11, v19
	v_mul_f32_e32 v62, v5, v23
	v_lshlrev_b32_e32 v63, 16, v24
	v_and_b32_e32 v24, 0xffff0000, v24
	v_lshlrev_b32_e32 v64, 16, v28
	v_and_b32_e32 v28, 0xffff0000, v28
	v_lshlrev_b32_e32 v67, 16, v26
	v_and_b32_e32 v26, 0xffff0000, v26
	v_lshlrev_b32_e32 v68, 16, v30
	v_and_b32_e32 v30, 0xffff0000, v30
	v_lshlrev_b32_e32 v69, 16, v27
	v_and_b32_e32 v27, 0xffff0000, v27
	v_lshlrev_b32_e32 v70, 16, v31
	v_and_b32_e32 v31, 0xffff0000, v31
	v_mul_f32_e32 v15, v3, v15
	v_fmac_f32_e32 v49, v3, v40
	v_mul_f32_e32 v33, v13, v33
	v_fmac_f32_e32 v50, v13, v42
	v_fmac_f32_e32 v51, v3, v16
	v_fmac_f32_e32 v52, v3, v43
	v_fmac_f32_e32 v53, v13, v20
	v_fmac_f32_e32 v54, v13, v44
	v_fmac_f32_e32 v55, v3, v17
	v_fmac_f32_e32 v56, v3, v45
	v_fmac_f32_e32 v57, v13, v21
	v_fmac_f32_e32 v58, v13, v46
	v_fmac_f32_e32 v59, v3, v18
	v_fmac_f32_e32 v61, v13, v22
	v_mul_f32_e32 v41, v125, v41
	v_mul_f32_e32 v38, v125, v38
	v_mul_f32_e32 v73, v11, v65
	v_mul_f32_e32 v74, v11, v25
	v_mul_f32_e32 v75, v5, v66
	v_mul_f32_e32 v76, v5, v29
	v_mul_f32_e32 v35, v126, v35
	v_mul_f32_e32 v37, v126, v37
	v_lshlrev_b32_e32 v39, 16, v39
	v_lshlrev_b32_e32 v36, 16, v36
	v_fmac_f32_e32 v60, v3, v47
	v_fmac_f32_e32 v62, v13, v48
	v_mul_f32_e32 v71, v11, v24
	v_mul_f32_e32 v72, v5, v28
	v_mul_f32_e32 v77, v11, v67
	v_mul_f32_e32 v78, v11, v26
	v_mul_f32_e32 v79, v5, v68
	v_mul_f32_e32 v80, v5, v30
	v_mul_f32_e32 v81, v11, v69
	v_mul_f32_e32 v82, v11, v27
	v_mul_f32_e32 v83, v5, v70
	v_mul_f32_e32 v84, v5, v31
	v_fmac_f32_e32 v15, v11, v40
	v_fmac_f32_e32 v49, v12, v43
	v_fmac_f32_e32 v33, v5, v42
	v_fmac_f32_e32 v50, v10, v44
	v_fmac_f32_e32 v51, v12, v17
	v_fmac_f32_e32 v52, v12, v45
	v_fmac_f32_e32 v53, v10, v21
	v_fmac_f32_e32 v54, v10, v46
	v_fmac_f32_e32 v55, v12, v18
	v_fmac_f32_e32 v56, v12, v47
	v_fmac_f32_e32 v57, v10, v22
	v_fmac_f32_e32 v58, v10, v48
	v_fmac_f32_e32 v59, v12, v19
	v_fmac_f32_e32 v61, v10, v23
	v_mul_f32_e32 v21, v3, v41
	v_mul_f32_e32 v22, v13, v38
	v_fmac_f32_e32 v73, v3, v24
	v_fmac_f32_e32 v74, v3, v65
	v_fmac_f32_e32 v75, v13, v28
	v_fmac_f32_e32 v76, v13, v66
	v_mul_f32_e32 v39, v126, v39
	v_mul_f32_e32 v36, v126, v36
	v_fmac_f32_e32 v60, v12, v35
	v_fmac_f32_e32 v62, v10, v37
	v_fmac_f32_e32 v71, v3, v63
	v_fmac_f32_e32 v72, v13, v64
; __device__ __forceinline__ void phase_hyconv(CP& p, char* smem) {
;     ...
; #pragma unroll
;     for (int s = 1; s < 4; ++s)
; #pragma unroll
;       for (int i = 0; i < 2; ++i) {
;         const int ch = tid + 256 * i;
;         unsigned e[8];
; #pragma unroll
;         for (int j = 0; j < 8; ++j) { const int idx = 8 * ch + s + j; e[j] = idx < 4096 ? (unsigned)cp[idx] : 0u; }
;         uint4 u; u.x = e[0] | (e[1] << 16); u.y = e[2] | (e[3] << 16); u.z = e[4] | (e[5] << 16); u.w = e[6] | (e[7] << 16);
;         *(uint4*)(cp + s * 4128 + 8 * ch) = u;
;       }
;     __syncthreads();
;     const bf16_t* abase = cp + si * 4128 + (2048 - i16 - si + 8 * g4);
;     f32x4 acc[4][4];
; #pragma unroll
;     for (int m = 0; m < 4; ++m)
; #pragma unroll
;       for (int n = 0; n < 4; ++n) acc[m][n] = (f32x4){0.f, 0.f, 0.f, 0.f};
;     for (int dl = -31; dl <= 31; ++dl) {
;       bf16x8 af[4][2];
; #pragma unroll
;       for (int mt = 0; mt < 4; ++mt)
; #pragma unroll
;         for (int kk = 0; kk < 2; ++kk) {
;           const bf16_t* ap = abase - 64 * dl - 16 * mt + 32 * kk;
;           const uint2 lo = *(const uint2*)ap, hi = *(const uint2*)(ap + 4);
;           union { uint4 u; bf16x8 v; } cv; cv.u.x = lo.x; cv.u.y = lo.y; cv.u.z = hi.x; cv.u.w = hi.y;
;           af[mt][kk] = cv.v;
;         }
; #pragma unroll
;       for (int jt = 0; jt < 4; ++jt) {
;         const int in0 = ocb + 16 * jt - 8 * dl;
;         if (in0 >= -8 && in0 <= 248) {
;           const bf16_t* bp = Vl + (in0 + 8 + i16) * 80 + 8 * g4;
;           const bf16x8 b0 = *(const bf16x8*)bp, b1 = *(const bf16x8*)(bp + 32);
	v_fmac_f32_e32 v77, v3, v25
	v_fmac_f32_e32 v78, v3, v67
	v_fmac_f32_e32 v79, v13, v29
	v_fmac_f32_e32 v80, v13, v68
	v_fmac_f32_e32 v81, v3, v26
	v_fmac_f32_e32 v82, v3, v69
	v_fmac_f32_e32 v83, v13, v30
	v_fmac_f32_e32 v84, v13, v70
	v_fmac_f32_e32 v15, v12, v16
	v_add_f32_e32 v16, v4, v49
	v_fmac_f32_e32 v33, v10, v20
	v_add_f32_e32 v17, v14, v50
	v_add_f32_e32 v18, v4, v51
	v_add_f32_e32 v19, v4, v52
	v_add_f32_e32 v20, v14, v53
	v_add_f32_e32 v23, v14, v54
	v_add_f32_e32 v35, v4, v55
	v_add_f32_e32 v37, v4, v56
	v_add_f32_e32 v38, v14, v57
	v_add_f32_e32 v40, v14, v58
	v_add_f32_e32 v41, v4, v59
	v_add_f32_e32 v43, v14, v61
	v_fmac_f32_e32 v21, v11, v63
	v_fmac_f32_e32 v22, v5, v64
	v_fmac_f32_e32 v73, v12, v25
	v_fmac_f32_e32 v74, v12, v67
	v_fmac_f32_e32 v75, v10, v29
	v_fmac_f32_e32 v76, v10, v68
	v_add_f32_e32 v42, v4, v60
	v_add_f32_e32 v44, v14, v62
	v_fmac_f32_e32 v71, v12, v65
	v_fmac_f32_e32 v72, v10, v66
	v_fmac_f32_e32 v77, v12, v26
	v_fmac_f32_e32 v78, v12, v69
	v_fmac_f32_e32 v79, v10, v30
	v_fmac_f32_e32 v80, v10, v70
	v_fmac_f32_e32 v81, v12, v27
	v_fmac_f32_e32 v82, v12, v39
	v_fmac_f32_e32 v83, v10, v31
	v_fmac_f32_e32 v84, v10, v36
	v_add_f32_e32 v15, v4, v15
	v_add_f32_e32 v25, v14, v33
	v_mul_f32_e32 v16, v16, v17
	v_mul_f32_e32 v17, v18, v20
	v_mul_f32_e32 v18, v19, v23
	v_mul_f32_e32 v19, v35, v38
	v_mul_f32_e32 v20, v37, v40
	v_mul_f32_e32 v23, v41, v43
	v_fmac_f32_e32 v21, v12, v24
	v_fmac_f32_e32 v22, v10, v28
	v_add_f32_e32 v28, v4, v73
	v_add_f32_e32 v29, v4, v74
	v_add_f32_e32 v30, v14, v75
	v_add_f32_e32 v31, v14, v76
	v_mul_f32_e32 v26, v42, v44
	v_add_f32_e32 v24, v4, v71
	v_add_f32_e32 v27, v14, v72
	v_add_f32_e32 v33, v4, v77
	v_add_f32_e32 v35, v4, v78
	v_add_f32_e32 v36, v14, v79
	v_add_f32_e32 v37, v14, v80
	v_add_f32_e32 v38, v4, v81
	v_add_f32_e32 v39, v4, v82
	v_add_f32_e32 v40, v14, v83
	v_add_f32_e32 v41, v14, v84
	v_mul_f32_e32 v15, v15, v25
	v_cvt_pk_bf16_f32 v17, v17, v18
	v_cvt_pk_bf16_f32 v18, v19, v20
	v_cvt_pk_bf16_f32 v19, v23, v26
	v_add_f32_e32 v20, v4, v21
	v_add_f32_e32 v21, v14, v22
	v_mul_f32_e32 v22, v28, v30
	v_mul_f32_e32 v23, v29, v31
	v_mul_f32_e32 v24, v24, v27
	v_mul_f32_e32 v25, v33, v36
	v_mul_f32_e32 v26, v35, v37
	v_mul_f32_e32 v27, v38, v40
	v_mul_f32_e32 v28, v39, v41
	v_cvt_pk_bf16_f32 v16, v15, v16
	v_mul_f32_e32 v15, v20, v21
	v_cvt_pk_bf16_f32 v21, v22, v23
	v_cvt_pk_bf16_f32 v22, v25, v26
	v_cvt_pk_bf16_f32 v23, v27, v28
	ds_write_b128 v32, v[16:19] offset:33024
	v_cvt_pk_bf16_f32 v20, v15, v24
	ds_write_b128 v34, v[20:23] offset:33024
	s_cbranch_scc0 .LBB0_2852
	s_and_saveexec_b64 s[46:47], vcc
	ds_write_b128 v139, v[6:9] offset:33024
	s_or_b64 exec, exec, s[46:47]
	v_mov_b32_e32 v4, 0
	v_mov_b32_e32 v3, 0
	s_waitcnt lgkmcnt(0)
	s_barrier
	ds_read_b128 v[16:19], v130
	ds_read_b64 v[20:21], v130 offset:16
	ds_read_b128 v[24:27], v130 offset:4096
	ds_read_b64 v[28:29], v130 offset:4112
	s_movk_i32 s48, 0xff
	v_cmp_eq_u32_e64 s[46:47], s48, v101
	s_waitcnt lgkmcnt(2)
	v_alignbit_b32 v32, v17, v16, 16
	v_alignbit_b32 v33, v18, v17, 16
	v_alignbit_b32 v34, v19, v18, 16
	v_alignbit_b32 v35, v20, v19, 16
	ds_write_b128 v130, v[32:35] offset:8256
	v_mov_b32_e32 v36, v17
	v_mov_b32_e32 v37, v18
	v_mov_b32_e32 v38, v19
	v_mov_b32_e32 v39, v20
	ds_write_b128 v130, v[36:39] offset:16512
	v_alignbit_b32 v40, v18, v17, 16
	v_alignbit_b32 v41, v19, v18, 16
	v_alignbit_b32 v42, v20, v19, 16
	v_alignbit_b32 v43, v21, v20, 16
	ds_write_b128 v130, v[40:43] offset:24768
	s_waitcnt lgkmcnt(3)
	v_cndmask_b32_e64 v28, v28, 0, s[46:47]
	v_cndmask_b32_e64 v29, v29, 0, s[46:47]
	v_alignbit_b32 v44, v25, v24, 16
	v_alignbit_b32 v45, v26, v25, 16
	v_alignbit_b32 v46, v27, v26, 16
	v_alignbit_b32 v47, v28, v27, 16
	ds_write_b128 v130, v[44:47] offset:12352
	v_mov_b32_e32 v48, v25
	v_mov_b32_e32 v49, v26
	v_mov_b32_e32 v50, v27
	v_mov_b32_e32 v51, v28
	ds_write_b128 v130, v[48:51] offset:20608
	v_alignbit_b32 v52, v26, v25, 16
	v_alignbit_b32 v53, v27, v26, 16
	v_alignbit_b32 v54, v28, v27, 16
	v_alignbit_b32 v55, v29, v28, 16
	ds_write_b128 v130, v[52:55] offset:28864
	v_mov_b32_e32 v4, v2
	v_mov_b32_e32 v5, v2
	v_mov_b32_e32 v3, v2
	v_mov_b64_e32 v[44:45], v[4:5]
	v_mov_b64_e32 v[48:49], v[4:5]
	v_mov_b64_e32 v[52:53], v[4:5]
	v_mov_b64_e32 v[56:57], v[4:5]
	v_mov_b64_e32 v[60:61], v[4:5]
	v_mov_b64_e32 v[64:65], v[4:5]
	v_mov_b64_e32 v[68:69], v[4:5]
	v_mov_b64_e32 v[72:73], v[4:5]
	v_mov_b64_e32 v[40:41], v[4:5]
	v_mov_b64_e32 v[36:37], v[4:5]
	v_mov_b64_e32 v[32:33], v[4:5]
	v_mov_b64_e32 v[28:29], v[4:5]
	v_mov_b64_e32 v[24:25], v[4:5]
	v_mov_b64_e32 v[20:21], v[4:5]
	v_mov_b64_e32 v[16:17], v[4:5]
	v_mov_b64_e32 v[12:13], v[4:5]
	v_mov_b32_e32 v140, v133
	v_mov_b32_e32 v141, v113
	v_mov_b64_e32 v[42:43], v[2:3]
	v_mov_b64_e32 v[46:47], v[2:3]
	v_mov_b64_e32 v[50:51], v[2:3]
	v_mov_b64_e32 v[54:55], v[2:3]
	v_mov_b64_e32 v[58:59], v[2:3]
	v_mov_b64_e32 v[62:63], v[2:3]
	v_mov_b64_e32 v[66:67], v[2:3]
	v_mov_b64_e32 v[70:71], v[2:3]
	v_mov_b64_e32 v[38:39], v[2:3]
	v_mov_b64_e32 v[34:35], v[2:3]
	v_mov_b64_e32 v[30:31], v[2:3]
	v_mov_b64_e32 v[26:27], v[2:3]
	v_mov_b64_e32 v[22:23], v[2:3]
	v_mov_b64_e32 v[18:19], v[2:3]
	v_mov_b64_e32 v[14:15], v[2:3]
	v_mov_b64_e32 v[10:11], v[2:3]
	s_waitcnt lgkmcnt(0)
	s_barrier
	v_readfirstlane_b32 s46, v124
	s_lshl_b32 s47, s46, 4
	s_mul_i32 s46, s46, 0xa0
	v_add_u32_e32 v234, v113, v128
	v_add_u32_e32 v235, v133, v128
	v_subrev_u32_e32 v234, s47, v234
	v_add_u32_e32 v235, 0x12100, v235
	v_subrev_u32_e32 v235, s46, v235
	s_mov_b32 s51, 0
	ds_read2_b64 v[74:77], v234 offset0:12 offset1:13
	ds_read2_b64 v[78:81], v234 offset0:8 offset1:9
	ds_read2_b64 v[94:97], v234 offset0:20 offset1:21
	ds_read2_b64 v[86:89], v234 offset0:16 offset1:17
	ds_read2_b64 v[90:93], v234 offset0:4 offset1:5
	ds_read2_b64 v[82:85], v234 offset1:1
	ds_read_b128 v[142:145], v235
	ds_read_b128 v[146:149], v235 offset:64
